# first-barrier census: 16 counter loads issued back to back, one wait
# speedup vs baseline: 1.0058x; 1.0058x over previous
; DI unsigned xb_ld(unsigned* p) { return __hip_atomic_load(p, __ATOMIC_RELAXED, __HIP_MEMORY_SCOPE_AGENT); }
; DI void xcd_barrier_complete(unsigned* bar, unsigned x, unsigned& nloc, unsigned& nx) {
;     ...
;   for (;;) {
;     sum = 0u; cnt = 0u; mine = 0u;
; #pragma unroll
;     for (unsigned j = 0; j < 16; ++j) { const unsigned c = xb_ld(&bar[XB_XCNT(j)]); sum += c; cnt += (c > 0u) ? 1u : 0u; mine = (j == x) ? c : mine; }
;     if (sum == G) break;
;     __builtin_amdgcn_s_sleep(1);
;     if ((++sp & 255u) == 0u) { if (xb_ld(&bar[XB_TMO])) break; if (sp > XB_SPIN_CAP) { atomicAdd(&bar[XB_TMO], 1u); break; } }
;   }
.LBB0_1792:
	v_readlane_b32 s6, v253, 42
	v_readlane_b32 s7, v253, 43
	v_readlane_b32 s5, v253, 39
	s_mov_b64 s[40:41], -1
	s_mov_b64 s[42:43], -1
	s_waitcnt lgkmcnt(0)
	s_nop 0
	global_load_dword v0, v183, s[6:7] sc1
	v_readlane_b32 s6, v253, 44
	v_readlane_b32 s7, v253, 45
	s_nop 4
	global_load_dword v1, v183, s[6:7] sc1
	v_readlane_b32 s6, v253, 46
	v_readlane_b32 s7, v253, 47
	s_nop 4
	global_load_dword v2, v183, s[6:7] sc1
	v_readlane_b32 s6, v253, 48
	v_readlane_b32 s7, v253, 49
	s_nop 4
	global_load_dword v3, v183, s[6:7] sc1
	v_readlane_b32 s6, v253, 50
	v_readlane_b32 s7, v253, 51
	s_nop 4
	global_load_dword v4, v183, s[6:7] sc1
	v_readlane_b32 s6, v253, 52
	v_readlane_b32 s7, v253, 53
	s_nop 4
	global_load_dword v5, v183, s[6:7] sc1
	v_readlane_b32 s6, v253, 54
	v_readlane_b32 s7, v253, 55
	s_nop 4
	global_load_dword v6, v183, s[6:7] sc1
	v_readlane_b32 s6, v253, 56
	v_readlane_b32 s7, v253, 57
	s_nop 4
	global_load_dword v7, v183, s[6:7] sc1
	v_readlane_b32 s6, v253, 58
	v_readlane_b32 s7, v253, 59
	s_nop 4
	global_load_dword v8, v183, s[6:7] sc1
	v_readlane_b32 s6, v253, 60
	v_readlane_b32 s7, v253, 61
	s_nop 4
	global_load_dword v9, v183, s[6:7] sc1
	v_readlane_b32 s6, v253, 62
	v_readlane_b32 s7, v253, 63
	s_nop 4
	global_load_dword v10, v183, s[6:7] sc1
	v_readlane_b32 s6, v254, 0
	v_readlane_b32 s7, v254, 1
	s_nop 4
	global_load_dword v11, v183, s[6:7] sc1
	v_readlane_b32 s6, v254, 2
	v_readlane_b32 s7, v254, 3
	s_nop 4
	global_load_dword v12, v183, s[6:7] sc1
	v_readlane_b32 s6, v254, 4
	v_readlane_b32 s7, v254, 5
	s_nop 4
	global_load_dword v13, v183, s[6:7] sc1
	v_readlane_b32 s6, v254, 6
	v_readlane_b32 s7, v254, 7
	s_nop 4
	global_load_dword v14, v183, s[6:7] sc1
	v_readlane_b32 s6, v254, 8
	v_readlane_b32 s7, v254, 9
	s_nop 4
	global_load_dword v15, v183, s[6:7] sc1
	s_waitcnt vmcnt(0)
	v_add_u32_e32 v16, v1, v0
	v_add_u32_e32 v16, v16, v2
	v_add_u32_e32 v16, v16, v3
	v_add_u32_e32 v16, v16, v4
	v_add_u32_e32 v16, v16, v5
	v_add_u32_e32 v16, v16, v6
	v_add_u32_e32 v16, v16, v7
	v_add_u32_e32 v16, v16, v8
	v_add_u32_e32 v16, v16, v9
	v_add_u32_e32 v16, v16, v10
	v_add_u32_e32 v16, v16, v11
	v_add_u32_e32 v16, v16, v12
	v_add_u32_e32 v16, v16, v13
	v_add_u32_e32 v16, v16, v14
	v_add_u32_e32 v16, v16, v15
	v_cmp_eq_u32_e32 vcc, s5, v16
	s_cbranch_vccnz .LBB0_1791
	s_and_b32 s5, s4, 0xff
	s_cmp_eq_u32 s5, 0
	s_mov_b64 s[44:45], -1
	s_sleep 1
	s_cbranch_scc1 .LBB0_1796
	s_and_b64 vcc, exec, s[44:45]
	s_cbranch_vccz .LBB0_1791
